# K-loop LDS-DMA addresses as scalar base plus lane offset, no per-lane 64-bit adds
# speedup vs baseline: 1.0133x; 1.0048x over previous
.LBB0_691:
	s_add_u32 s57, s10, 0x100
	s_addc_u32 vcc_lo, s11, 0
	s_add_u32 s38, s52, 0x80
	s_addc_u32 s39, s53, 0
	s_mov_b32 s10, 0
	s_add_i32 s52, s10, 2
	s_add_u32 s33, s38, 0x80
	s_addc_u32 s11, s39, 0
	s_add_i32 s34, 0, 0x10000
	s_cmp_eq_u32 s95, s10
	s_cselect_b32 s11, s9, s11
	s_cselect_b32 s10, s8, s33
	s_cselect_b32 s73, s1, vcc_lo
	s_cselect_b32 s72, s0, s57
	s_add_i32 s33, 0, 0x14000
	v_add_u32_e32 v156, s34, v223
	v_add_u32_e32 v172, s33, v223
	ds_read_b128 v[130:133], v156
	ds_read_b128 v[134:137], v156 offset:1024
	ds_read_b128 v[138:141], v156 offset:2048
	ds_read_b128 v[156:159], v156 offset:3072
	ds_read_b128 v[160:163], v172
	ds_read_b128 v[164:167], v172 offset:1024
	ds_read_b128 v[168:171], v172 offset:2048
	ds_read_b128 v[172:175], v172 offset:3072
	s_add_i32 m0, s20, 0xc000
	ds_read_b128 v[176:179], v225
	ds_read_b128 v[180:183], v225 offset:1024
	ds_read_b128 v[184:187], v225 offset:2048
	ds_read_b128 v[188:191], v225 offset:3072
	ds_read_b128 v[192:195], v225 offset:4096
	ds_read_b128 v[196:199], v225 offset:5120
	ds_read_b128 v[200:203], v225 offset:6144
	ds_read_b128 v[226:229], v225 offset:7168
	global_load_lds_dwordx4 v154, s[38:39]
	s_add_i32 m0, s20, 0xe000
	s_nop 0
	global_load_lds_dwordx4 v152, s[38:39]
	s_waitcnt vmcnt(8)
	s_waitcnt lgkmcnt(0)
	s_barrier
	s_setprio 1
	s_waitcnt lgkmcnt(0)
	v_mfma_f32_16x16x32_bf16 v[126:129], v[130:133], v[176:179], 0
	v_mfma_f32_16x16x32_bf16 v[122:125], v[138:141], v[176:179], 0
	v_mfma_f32_16x16x32_bf16 v[110:113], v[130:133], v[184:187], 0
	v_mfma_f32_16x16x32_bf16 v[106:109], v[138:141], v[184:187], 0
	v_mfma_f32_16x16x32_bf16 v[94:97], v[130:133], v[192:195], 0
	v_mfma_f32_16x16x32_bf16 v[90:93], v[138:141], v[192:195], 0
	v_mfma_f32_16x16x32_bf16 v[78:81], v[130:133], v[200:203], 0
	v_mfma_f32_16x16x32_bf16 v[74:77], v[138:141], v[200:203], 0
	v_mfma_f32_16x16x32_bf16 v[126:129], v[134:137], v[180:183], v[126:129]
	v_mfma_f32_16x16x32_bf16 v[122:125], v[156:159], v[180:183], v[122:125]
	v_mfma_f32_16x16x32_bf16 v[110:113], v[134:137], v[188:191], v[110:113]
	v_mfma_f32_16x16x32_bf16 v[106:109], v[156:159], v[188:191], v[106:109]
	v_mfma_f32_16x16x32_bf16 v[94:97], v[134:137], v[196:199], v[94:97]
	v_mfma_f32_16x16x32_bf16 v[90:93], v[156:159], v[196:199], v[90:93]
	v_mfma_f32_16x16x32_bf16 v[78:81], v[134:137], v[226:229], v[78:81]
	v_mfma_f32_16x16x32_bf16 v[74:77], v[156:159], v[226:229], v[74:77]
	s_setprio 0
	s_setprio 1
	v_mfma_f32_16x16x32_bf16 v[118:121], v[160:163], v[176:179], 0
	v_mfma_f32_16x16x32_bf16 v[114:117], v[168:171], v[176:179], 0
	v_mfma_f32_16x16x32_bf16 v[102:105], v[160:163], v[184:187], 0
	v_mfma_f32_16x16x32_bf16 v[98:101], v[168:171], v[184:187], 0
	v_mfma_f32_16x16x32_bf16 v[86:89], v[160:163], v[192:195], 0
	v_mfma_f32_16x16x32_bf16 v[82:85], v[168:171], v[192:195], 0
	v_mfma_f32_16x16x32_bf16 v[70:73], v[160:163], v[200:203], 0
	v_mfma_f32_16x16x32_bf16 v[66:69], v[168:171], v[200:203], 0
	v_mfma_f32_16x16x32_bf16 v[118:121], v[164:167], v[180:183], v[118:121]
	v_mfma_f32_16x16x32_bf16 v[114:117], v[172:175], v[180:183], v[114:117]
	v_mfma_f32_16x16x32_bf16 v[102:105], v[164:167], v[188:191], v[102:105]
	v_mfma_f32_16x16x32_bf16 v[98:101], v[172:175], v[188:191], v[98:101]
	v_mfma_f32_16x16x32_bf16 v[86:89], v[164:167], v[196:199], v[86:89]
	v_mfma_f32_16x16x32_bf16 v[82:85], v[172:175], v[196:199], v[82:85]
	v_mfma_f32_16x16x32_bf16 v[70:73], v[164:167], v[226:229], v[70:73]
	v_mfma_f32_16x16x32_bf16 v[66:69], v[172:175], v[226:229], v[66:69]
	s_setprio 0
	s_barrier
	s_add_i32 s34, s34, s29
	s_mov_b32 m0, s34
	ds_read_b128 v[176:179], v225 offset:16384
	ds_read_b128 v[180:183], v225 offset:17408
	ds_read_b128 v[184:187], v225 offset:18432
	ds_read_b128 v[188:191], v225 offset:19456
	ds_read_b128 v[192:195], v225 offset:20480
	ds_read_b128 v[196:199], v225 offset:21504
	ds_read_b128 v[200:203], v225 offset:22528
	ds_read_b128 v[226:229], v225 offset:23552
	global_load_lds_dwordx4 v0, s[72:73]
	s_add_i32 m0, s34, 0x2000
	s_mov_b64 s[98:99], s[72:73]
	s_add_i32 s33, s33, s29
	global_load_lds_dwordx4 v150, s[72:73]
	s_add_u32 s72, s72, s46
	s_addc_u32 s73, s73, 0
	s_mov_b32 m0, s33
	s_mov_b64 s[100:101], s[10:11]
	global_load_lds_dwordx4 v0, s[72:73]
	s_add_i32 m0, s33, 0x2000
	s_nop 0
	global_load_lds_dwordx4 v150, s[72:73]
	s_mov_b32 m0, s20
	s_nop 0
	global_load_lds_dwordx4 v146, s[10:11]
	s_mov_b32 m0, s35
	s_nop 0
	global_load_lds_dwordx4 v148, s[10:11]
	s_waitcnt vmcnt(8)
	s_waitcnt lgkmcnt(0)
	s_barrier
	s_setprio 1
	s_waitcnt lgkmcnt(0)
	v_mfma_f32_16x16x32_bf16 v[62:65], v[130:133], v[176:179], 0
	v_mfma_f32_16x16x32_bf16 v[58:61], v[138:141], v[176:179], 0
	v_mfma_f32_16x16x32_bf16 v[46:49], v[130:133], v[184:187], 0
	v_mfma_f32_16x16x32_bf16 v[42:45], v[138:141], v[184:187], 0
	v_mfma_f32_16x16x32_bf16 v[30:33], v[130:133], v[192:195], 0
	v_mfma_f32_16x16x32_bf16 v[26:29], v[138:141], v[192:195], 0
	v_mfma_f32_16x16x32_bf16 v[14:17], v[130:133], v[200:203], 0
	v_mfma_f32_16x16x32_bf16 v[10:13], v[138:141], v[200:203], 0
	v_mfma_f32_16x16x32_bf16 v[62:65], v[134:137], v[180:183], v[62:65]
	v_mfma_f32_16x16x32_bf16 v[58:61], v[156:159], v[180:183], v[58:61]
	v_mfma_f32_16x16x32_bf16 v[46:49], v[134:137], v[188:191], v[46:49]
	v_mfma_f32_16x16x32_bf16 v[42:45], v[156:159], v[188:191], v[42:45]
	v_mfma_f32_16x16x32_bf16 v[30:33], v[134:137], v[196:199], v[30:33]
	v_mfma_f32_16x16x32_bf16 v[26:29], v[156:159], v[196:199], v[26:29]
	v_mfma_f32_16x16x32_bf16 v[14:17], v[134:137], v[226:229], v[14:17]
	v_mfma_f32_16x16x32_bf16 v[10:13], v[156:159], v[226:229], v[10:13]
	s_setprio 0
	s_setprio 1
	v_mfma_f32_16x16x32_bf16 v[54:57], v[160:163], v[176:179], 0
	v_mfma_f32_16x16x32_bf16 v[50:53], v[168:171], v[176:179], 0
	v_mfma_f32_16x16x32_bf16 v[38:41], v[160:163], v[184:187], 0
	v_mfma_f32_16x16x32_bf16 v[34:37], v[168:171], v[184:187], 0
	v_mfma_f32_16x16x32_bf16 v[22:25], v[160:163], v[192:195], 0
	v_mfma_f32_16x16x32_bf16 v[18:21], v[168:171], v[192:195], 0
	v_mfma_f32_16x16x32_bf16 v[6:9], v[160:163], v[200:203], 0
	v_mfma_f32_16x16x32_bf16 v[2:5], v[168:171], v[200:203], 0
	v_mfma_f32_16x16x32_bf16 v[54:57], v[164:167], v[180:183], v[54:57]
	v_mfma_f32_16x16x32_bf16 v[50:53], v[172:175], v[180:183], v[50:53]
	v_mfma_f32_16x16x32_bf16 v[38:41], v[164:167], v[188:191], v[38:41]
	v_mfma_f32_16x16x32_bf16 v[34:37], v[172:175], v[188:191], v[34:37]
	v_mfma_f32_16x16x32_bf16 v[22:25], v[164:167], v[196:199], v[22:25]
	v_mfma_f32_16x16x32_bf16 v[18:21], v[172:175], v[196:199], v[18:21]
	v_mfma_f32_16x16x32_bf16 v[6:9], v[164:167], v[226:229], v[6:9]
	v_mfma_f32_16x16x32_bf16 v[2:5], v[172:175], v[226:229], v[2:5]
	s_setprio 0
	s_barrier
	s_add_i32 s33, 0, 0x18000
	s_add_i32 s34, 0, 0x1c000
	v_add_u32_e32 v156, s33, v223
	v_add_u32_e32 v172, s34, v223
	ds_read_b128 v[130:133], v156
	ds_read_b128 v[134:137], v156 offset:1024
	ds_read_b128 v[138:141], v156 offset:2048
	ds_read_b128 v[156:159], v156 offset:3072
	ds_read_b128 v[160:163], v172
	ds_read_b128 v[164:167], v172 offset:1024
	ds_read_b128 v[168:171], v172 offset:2048
	ds_read_b128 v[172:175], v172 offset:3072
	s_add_u32 s10, s10, s46
	s_addc_u32 s11, s11, 0
	s_mov_b32 m0, s93
	ds_read_b128 v[176:179], v225 offset:32768
	ds_read_b128 v[180:183], v225 offset:33792
	ds_read_b128 v[184:187], v225 offset:34816
	ds_read_b128 v[188:191], v225 offset:35840
	ds_read_b128 v[192:195], v225 offset:36864
	ds_read_b128 v[196:199], v225 offset:37888
	ds_read_b128 v[200:203], v225 offset:38912
	ds_read_b128 v[226:229], v225 offset:39936
	global_load_lds_dwordx4 v146, s[10:11]
	s_mov_b32 m0, s83
	s_nop 0
	global_load_lds_dwordx4 v148, s[10:11]
	s_waitcnt vmcnt(8)
	s_waitcnt lgkmcnt(0)
	s_barrier
	s_setprio 1
	s_waitcnt lgkmcnt(0)
	v_mfma_f32_16x16x32_bf16 v[126:129], v[130:133], v[176:179], v[126:129]
	v_mfma_f32_16x16x32_bf16 v[122:125], v[138:141], v[176:179], v[122:125]
	v_mfma_f32_16x16x32_bf16 v[110:113], v[130:133], v[184:187], v[110:113]
	v_mfma_f32_16x16x32_bf16 v[106:109], v[138:141], v[184:187], v[106:109]
	v_mfma_f32_16x16x32_bf16 v[94:97], v[130:133], v[192:195], v[94:97]
	v_mfma_f32_16x16x32_bf16 v[90:93], v[138:141], v[192:195], v[90:93]
	v_mfma_f32_16x16x32_bf16 v[78:81], v[130:133], v[200:203], v[78:81]
	v_mfma_f32_16x16x32_bf16 v[74:77], v[138:141], v[200:203], v[74:77]
	v_mfma_f32_16x16x32_bf16 v[126:129], v[134:137], v[180:183], v[126:129]
	v_mfma_f32_16x16x32_bf16 v[122:125], v[156:159], v[180:183], v[122:125]
	v_mfma_f32_16x16x32_bf16 v[110:113], v[134:137], v[188:191], v[110:113]
	v_mfma_f32_16x16x32_bf16 v[106:109], v[156:159], v[188:191], v[106:109]
	v_mfma_f32_16x16x32_bf16 v[94:97], v[134:137], v[196:199], v[94:97]
	v_mfma_f32_16x16x32_bf16 v[90:93], v[156:159], v[196:199], v[90:93]
	v_mfma_f32_16x16x32_bf16 v[78:81], v[134:137], v[226:229], v[78:81]
	v_mfma_f32_16x16x32_bf16 v[74:77], v[156:159], v[226:229], v[74:77]
	s_setprio 0
	s_setprio 1
	v_mfma_f32_16x16x32_bf16 v[118:121], v[160:163], v[176:179], v[118:121]
	v_mfma_f32_16x16x32_bf16 v[114:117], v[168:171], v[176:179], v[114:117]
	v_mfma_f32_16x16x32_bf16 v[102:105], v[160:163], v[184:187], v[102:105]
	v_mfma_f32_16x16x32_bf16 v[98:101], v[168:171], v[184:187], v[98:101]
	v_mfma_f32_16x16x32_bf16 v[86:89], v[160:163], v[192:195], v[86:89]
	v_mfma_f32_16x16x32_bf16 v[82:85], v[168:171], v[192:195], v[82:85]
	v_mfma_f32_16x16x32_bf16 v[70:73], v[160:163], v[200:203], v[70:73]
	v_mfma_f32_16x16x32_bf16 v[66:69], v[168:171], v[200:203], v[66:69]
	v_mfma_f32_16x16x32_bf16 v[118:121], v[164:167], v[180:183], v[118:121]
	v_mfma_f32_16x16x32_bf16 v[114:117], v[172:175], v[180:183], v[114:117]
	v_mfma_f32_16x16x32_bf16 v[102:105], v[164:167], v[188:191], v[102:105]
	v_mfma_f32_16x16x32_bf16 v[98:101], v[172:175], v[188:191], v[98:101]
	v_mfma_f32_16x16x32_bf16 v[86:89], v[164:167], v[196:199], v[86:89]
	v_mfma_f32_16x16x32_bf16 v[82:85], v[172:175], v[196:199], v[82:85]
	v_mfma_f32_16x16x32_bf16 v[70:73], v[164:167], v[226:229], v[70:73]
	v_mfma_f32_16x16x32_bf16 v[66:69], v[172:175], v[226:229], v[66:69]
	s_setprio 0
	s_barrier
	s_add_i32 s10, s33, s29
	s_mov_b32 m0, s10
	s_add_u32 s98, s98, 0x80
	s_addc_u32 s99, s99, 0
	ds_read_b128 v[176:179], v225 offset:49152
	ds_read_b128 v[180:183], v225 offset:50176
	ds_read_b128 v[184:187], v225 offset:51200
	ds_read_b128 v[188:191], v225 offset:52224
	ds_read_b128 v[192:195], v225 offset:53248
	ds_read_b128 v[196:199], v225 offset:54272
	ds_read_b128 v[200:203], v225 offset:55296
	ds_read_b128 v[226:229], v225 offset:56320
	global_load_lds_dwordx4 v0, s[98:99]
	s_add_i32 m0, s10, 0x2000
	s_add_i32 s10, s34, s29
	global_load_lds_dwordx4 v150, s[98:99]
	s_mov_b32 m0, s10
	s_add_u32 s72, s72, 0x80
	s_addc_u32 s73, s73, 0
	global_load_lds_dwordx4 v0, s[72:73]
	s_add_i32 m0, s10, 0x2000
	s_add_u32 s100, s100, 0x80
	s_addc_u32 s101, s101, 0
	global_load_lds_dwordx4 v150, s[72:73]
	s_mov_b32 m0, s96
	s_nop 0
	global_load_lds_dwordx4 v146, s[100:101]
	s_mov_b32 m0, s97
	s_nop 0
	global_load_lds_dwordx4 v148, s[100:101]
	s_waitcnt vmcnt(8)
	s_waitcnt lgkmcnt(0)
	s_barrier
	s_setprio 1
	s_waitcnt lgkmcnt(0)
	v_mfma_f32_16x16x32_bf16 v[62:65], v[130:133], v[176:179], v[62:65]
	v_mfma_f32_16x16x32_bf16 v[58:61], v[138:141], v[176:179], v[58:61]
	v_mfma_f32_16x16x32_bf16 v[46:49], v[130:133], v[184:187], v[46:49]
	v_mfma_f32_16x16x32_bf16 v[42:45], v[138:141], v[184:187], v[42:45]
	v_mfma_f32_16x16x32_bf16 v[30:33], v[130:133], v[192:195], v[30:33]
	v_mfma_f32_16x16x32_bf16 v[26:29], v[138:141], v[192:195], v[26:29]
	v_mfma_f32_16x16x32_bf16 v[14:17], v[130:133], v[200:203], v[14:17]
	v_mfma_f32_16x16x32_bf16 v[10:13], v[138:141], v[200:203], v[10:13]
	v_mfma_f32_16x16x32_bf16 v[62:65], v[134:137], v[180:183], v[62:65]
	v_mfma_f32_16x16x32_bf16 v[58:61], v[156:159], v[180:183], v[58:61]
	v_mfma_f32_16x16x32_bf16 v[46:49], v[134:137], v[188:191], v[46:49]
	v_mfma_f32_16x16x32_bf16 v[42:45], v[156:159], v[188:191], v[42:45]
	v_mfma_f32_16x16x32_bf16 v[30:33], v[134:137], v[196:199], v[30:33]
	v_mfma_f32_16x16x32_bf16 v[26:29], v[156:159], v[196:199], v[26:29]
	v_mfma_f32_16x16x32_bf16 v[14:17], v[134:137], v[226:229], v[14:17]
	v_mfma_f32_16x16x32_bf16 v[10:13], v[156:159], v[226:229], v[10:13]
	s_setprio 0
	s_setprio 1
	v_mfma_f32_16x16x32_bf16 v[54:57], v[160:163], v[176:179], v[54:57]
	v_mfma_f32_16x16x32_bf16 v[50:53], v[168:171], v[176:179], v[50:53]
	v_mfma_f32_16x16x32_bf16 v[38:41], v[160:163], v[184:187], v[38:41]
	v_mfma_f32_16x16x32_bf16 v[34:37], v[168:171], v[184:187], v[34:37]
	v_mfma_f32_16x16x32_bf16 v[22:25], v[160:163], v[192:195], v[22:25]
	v_mfma_f32_16x16x32_bf16 v[18:21], v[168:171], v[192:195], v[18:21]
	v_mfma_f32_16x16x32_bf16 v[6:9], v[160:163], v[200:203], v[6:9]
	v_mfma_f32_16x16x32_bf16 v[2:5], v[168:171], v[200:203], v[2:5]
	v_mfma_f32_16x16x32_bf16 v[54:57], v[164:167], v[180:183], v[54:57]
	v_mfma_f32_16x16x32_bf16 v[50:53], v[172:175], v[180:183], v[50:53]
	v_mfma_f32_16x16x32_bf16 v[38:41], v[164:167], v[188:191], v[38:41]
	v_mfma_f32_16x16x32_bf16 v[34:37], v[172:175], v[188:191], v[34:37]
	v_mfma_f32_16x16x32_bf16 v[22:25], v[164:167], v[196:199], v[22:25]
	v_mfma_f32_16x16x32_bf16 v[18:21], v[172:175], v[196:199], v[18:21]
	v_mfma_f32_16x16x32_bf16 v[6:9], v[164:167], v[226:229], v[6:9]
	v_mfma_f32_16x16x32_bf16 v[2:5], v[172:175], v[226:229], v[2:5]
	s_setprio 0
	s_barrier
	s_add_u32 s57, s57, 0x100
	s_addc_u32 vcc_lo, vcc_lo, 0
	s_add_u32 s38, s38, 0x100
	s_addc_u32 s39, s39, 0
	s_cmp_ge_u32 s52, s22
	s_mov_b32 s10, s52
	s_cbranch_scc0 .LBB0_692
	s_branch .Lkloop_exit
.LBB0_692:
	s_add_i32 s52, s10, 2
	s_add_u32 s33, s38, 0x80
	s_addc_u32 s11, s39, 0
	s_add_i32 s34, 0, 0x10000
	s_cmp_eq_u32 s95, s10
	s_cselect_b32 s11, s9, s11
	s_cselect_b32 s10, s8, s33
	s_cselect_b32 s73, s1, vcc_lo
	s_cselect_b32 s72, s0, s57
	s_add_i32 s33, 0, 0x14000
	v_add_u32_e32 v156, s34, v223
	v_add_u32_e32 v172, s33, v223
	ds_read_b128 v[130:133], v156
	ds_read_b128 v[134:137], v156 offset:1024
	ds_read_b128 v[138:141], v156 offset:2048
	ds_read_b128 v[156:159], v156 offset:3072
	ds_read_b128 v[160:163], v172
	ds_read_b128 v[164:167], v172 offset:1024
	ds_read_b128 v[168:171], v172 offset:2048
	ds_read_b128 v[172:175], v172 offset:3072
	s_add_i32 m0, s20, 0xc000
	ds_read_b128 v[176:179], v225
	ds_read_b128 v[180:183], v225 offset:1024
	ds_read_b128 v[184:187], v225 offset:2048
	ds_read_b128 v[188:191], v225 offset:3072
	ds_read_b128 v[192:195], v225 offset:4096
	ds_read_b128 v[196:199], v225 offset:5120
	ds_read_b128 v[200:203], v225 offset:6144
	ds_read_b128 v[226:229], v225 offset:7168
	global_load_lds_dwordx4 v154, s[38:39]
	s_add_i32 m0, s20, 0xe000
	s_nop 0
	global_load_lds_dwordx4 v152, s[38:39]
	s_waitcnt vmcnt(8)
	s_waitcnt lgkmcnt(0)
	s_barrier
	s_setprio 1
	s_waitcnt lgkmcnt(0)
	v_mfma_f32_16x16x32_bf16 v[126:129], v[130:133], v[176:179], v[126:129]
	v_mfma_f32_16x16x32_bf16 v[122:125], v[138:141], v[176:179], v[122:125]
	v_mfma_f32_16x16x32_bf16 v[110:113], v[130:133], v[184:187], v[110:113]
	v_mfma_f32_16x16x32_bf16 v[106:109], v[138:141], v[184:187], v[106:109]
	v_mfma_f32_16x16x32_bf16 v[94:97], v[130:133], v[192:195], v[94:97]
	v_mfma_f32_16x16x32_bf16 v[90:93], v[138:141], v[192:195], v[90:93]
	v_mfma_f32_16x16x32_bf16 v[78:81], v[130:133], v[200:203], v[78:81]
	v_mfma_f32_16x16x32_bf16 v[74:77], v[138:141], v[200:203], v[74:77]
	v_mfma_f32_16x16x32_bf16 v[126:129], v[134:137], v[180:183], v[126:129]
	v_mfma_f32_16x16x32_bf16 v[122:125], v[156:159], v[180:183], v[122:125]
	v_mfma_f32_16x16x32_bf16 v[110:113], v[134:137], v[188:191], v[110:113]
	v_mfma_f32_16x16x32_bf16 v[106:109], v[156:159], v[188:191], v[106:109]
	v_mfma_f32_16x16x32_bf16 v[94:97], v[134:137], v[196:199], v[94:97]
	v_mfma_f32_16x16x32_bf16 v[90:93], v[156:159], v[196:199], v[90:93]
	v_mfma_f32_16x16x32_bf16 v[78:81], v[134:137], v[226:229], v[78:81]
	v_mfma_f32_16x16x32_bf16 v[74:77], v[156:159], v[226:229], v[74:77]
	s_setprio 0
	s_setprio 1
	v_mfma_f32_16x16x32_bf16 v[118:121], v[160:163], v[176:179], v[118:121]
	v_mfma_f32_16x16x32_bf16 v[114:117], v[168:171], v[176:179], v[114:117]
	v_mfma_f32_16x16x32_bf16 v[102:105], v[160:163], v[184:187], v[102:105]
	v_mfma_f32_16x16x32_bf16 v[98:101], v[168:171], v[184:187], v[98:101]
	v_mfma_f32_16x16x32_bf16 v[86:89], v[160:163], v[192:195], v[86:89]
	v_mfma_f32_16x16x32_bf16 v[82:85], v[168:171], v[192:195], v[82:85]
	v_mfma_f32_16x16x32_bf16 v[70:73], v[160:163], v[200:203], v[70:73]
	v_mfma_f32_16x16x32_bf16 v[66:69], v[168:171], v[200:203], v[66:69]
	v_mfma_f32_16x16x32_bf16 v[118:121], v[164:167], v[180:183], v[118:121]
	v_mfma_f32_16x16x32_bf16 v[114:117], v[172:175], v[180:183], v[114:117]
	v_mfma_f32_16x16x32_bf16 v[102:105], v[164:167], v[188:191], v[102:105]
	v_mfma_f32_16x16x32_bf16 v[98:101], v[172:175], v[188:191], v[98:101]
	v_mfma_f32_16x16x32_bf16 v[86:89], v[164:167], v[196:199], v[86:89]
	v_mfma_f32_16x16x32_bf16 v[82:85], v[172:175], v[196:199], v[82:85]
	v_mfma_f32_16x16x32_bf16 v[70:73], v[164:167], v[226:229], v[70:73]
	v_mfma_f32_16x16x32_bf16 v[66:69], v[172:175], v[226:229], v[66:69]
	s_setprio 0
	s_barrier
	s_add_i32 s34, s34, s29
	s_mov_b32 m0, s34
	ds_read_b128 v[176:179], v225 offset:16384
	ds_read_b128 v[180:183], v225 offset:17408
	ds_read_b128 v[184:187], v225 offset:18432
	ds_read_b128 v[188:191], v225 offset:19456
	ds_read_b128 v[192:195], v225 offset:20480
	ds_read_b128 v[196:199], v225 offset:21504
	ds_read_b128 v[200:203], v225 offset:22528
	ds_read_b128 v[226:229], v225 offset:23552
	global_load_lds_dwordx4 v0, s[72:73]
	s_add_i32 m0, s34, 0x2000
	s_mov_b64 s[98:99], s[72:73]
	s_add_i32 s33, s33, s29
	global_load_lds_dwordx4 v150, s[72:73]
	s_add_u32 s72, s72, s46
	s_addc_u32 s73, s73, 0
	s_mov_b32 m0, s33
	s_mov_b64 s[100:101], s[10:11]
	global_load_lds_dwordx4 v0, s[72:73]
	s_add_i32 m0, s33, 0x2000
	s_nop 0
	global_load_lds_dwordx4 v150, s[72:73]
	s_mov_b32 m0, s20
	s_nop 0
	global_load_lds_dwordx4 v146, s[10:11]
	s_mov_b32 m0, s35
	s_nop 0
	global_load_lds_dwordx4 v148, s[10:11]
	s_waitcnt vmcnt(8)
	s_waitcnt lgkmcnt(0)
	s_barrier
	s_setprio 1
	s_waitcnt lgkmcnt(0)
	v_mfma_f32_16x16x32_bf16 v[62:65], v[130:133], v[176:179], v[62:65]
	v_mfma_f32_16x16x32_bf16 v[58:61], v[138:141], v[176:179], v[58:61]
	v_mfma_f32_16x16x32_bf16 v[46:49], v[130:133], v[184:187], v[46:49]
	v_mfma_f32_16x16x32_bf16 v[42:45], v[138:141], v[184:187], v[42:45]
	v_mfma_f32_16x16x32_bf16 v[30:33], v[130:133], v[192:195], v[30:33]
	v_mfma_f32_16x16x32_bf16 v[26:29], v[138:141], v[192:195], v[26:29]
	v_mfma_f32_16x16x32_bf16 v[14:17], v[130:133], v[200:203], v[14:17]
	v_mfma_f32_16x16x32_bf16 v[10:13], v[138:141], v[200:203], v[10:13]
	v_mfma_f32_16x16x32_bf16 v[62:65], v[134:137], v[180:183], v[62:65]
	v_mfma_f32_16x16x32_bf16 v[58:61], v[156:159], v[180:183], v[58:61]
	v_mfma_f32_16x16x32_bf16 v[46:49], v[134:137], v[188:191], v[46:49]
	v_mfma_f32_16x16x32_bf16 v[42:45], v[156:159], v[188:191], v[42:45]
	v_mfma_f32_16x16x32_bf16 v[30:33], v[134:137], v[196:199], v[30:33]
	v_mfma_f32_16x16x32_bf16 v[26:29], v[156:159], v[196:199], v[26:29]
	v_mfma_f32_16x16x32_bf16 v[14:17], v[134:137], v[226:229], v[14:17]
	v_mfma_f32_16x16x32_bf16 v[10:13], v[156:159], v[226:229], v[10:13]
	s_setprio 0
	s_setprio 1
	v_mfma_f32_16x16x32_bf16 v[54:57], v[160:163], v[176:179], v[54:57]
	v_mfma_f32_16x16x32_bf16 v[50:53], v[168:171], v[176:179], v[50:53]
	v_mfma_f32_16x16x32_bf16 v[38:41], v[160:163], v[184:187], v[38:41]
	v_mfma_f32_16x16x32_bf16 v[34:37], v[168:171], v[184:187], v[34:37]
	v_mfma_f32_16x16x32_bf16 v[22:25], v[160:163], v[192:195], v[22:25]
	v_mfma_f32_16x16x32_bf16 v[18:21], v[168:171], v[192:195], v[18:21]
	v_mfma_f32_16x16x32_bf16 v[6:9], v[160:163], v[200:203], v[6:9]
	v_mfma_f32_16x16x32_bf16 v[2:5], v[168:171], v[200:203], v[2:5]
	v_mfma_f32_16x16x32_bf16 v[54:57], v[164:167], v[180:183], v[54:57]
	v_mfma_f32_16x16x32_bf16 v[50:53], v[172:175], v[180:183], v[50:53]
	v_mfma_f32_16x16x32_bf16 v[38:41], v[164:167], v[188:191], v[38:41]
	v_mfma_f32_16x16x32_bf16 v[34:37], v[172:175], v[188:191], v[34:37]
	v_mfma_f32_16x16x32_bf16 v[22:25], v[164:167], v[196:199], v[22:25]
	v_mfma_f32_16x16x32_bf16 v[18:21], v[172:175], v[196:199], v[18:21]
	v_mfma_f32_16x16x32_bf16 v[6:9], v[164:167], v[226:229], v[6:9]
	v_mfma_f32_16x16x32_bf16 v[2:5], v[172:175], v[226:229], v[2:5]
	s_setprio 0
	s_barrier
	s_add_i32 s33, 0, 0x18000
	s_add_i32 s34, 0, 0x1c000
	v_add_u32_e32 v156, s33, v223
	v_add_u32_e32 v172, s34, v223
	ds_read_b128 v[130:133], v156
	ds_read_b128 v[134:137], v156 offset:1024
	ds_read_b128 v[138:141], v156 offset:2048
	ds_read_b128 v[156:159], v156 offset:3072
	ds_read_b128 v[160:163], v172
	ds_read_b128 v[164:167], v172 offset:1024
	ds_read_b128 v[168:171], v172 offset:2048
	ds_read_b128 v[172:175], v172 offset:3072
	s_add_u32 s10, s10, s46
	s_addc_u32 s11, s11, 0
	s_mov_b32 m0, s93
	ds_read_b128 v[176:179], v225 offset:32768
	ds_read_b128 v[180:183], v225 offset:33792
	ds_read_b128 v[184:187], v225 offset:34816
	ds_read_b128 v[188:191], v225 offset:35840
	ds_read_b128 v[192:195], v225 offset:36864
	ds_read_b128 v[196:199], v225 offset:37888
	ds_read_b128 v[200:203], v225 offset:38912
	ds_read_b128 v[226:229], v225 offset:39936
	global_load_lds_dwordx4 v146, s[10:11]
	s_mov_b32 m0, s83
	s_nop 0
	global_load_lds_dwordx4 v148, s[10:11]
	s_waitcnt vmcnt(8)
	s_waitcnt lgkmcnt(0)
	s_barrier
	s_setprio 1
	s_waitcnt lgkmcnt(0)
	v_mfma_f32_16x16x32_bf16 v[126:129], v[130:133], v[176:179], v[126:129]
	v_mfma_f32_16x16x32_bf16 v[122:125], v[138:141], v[176:179], v[122:125]
	v_mfma_f32_16x16x32_bf16 v[110:113], v[130:133], v[184:187], v[110:113]
	v_mfma_f32_16x16x32_bf16 v[106:109], v[138:141], v[184:187], v[106:109]
	v_mfma_f32_16x16x32_bf16 v[94:97], v[130:133], v[192:195], v[94:97]
	v_mfma_f32_16x16x32_bf16 v[90:93], v[138:141], v[192:195], v[90:93]
	v_mfma_f32_16x16x32_bf16 v[78:81], v[130:133], v[200:203], v[78:81]
	v_mfma_f32_16x16x32_bf16 v[74:77], v[138:141], v[200:203], v[74:77]
	v_mfma_f32_16x16x32_bf16 v[126:129], v[134:137], v[180:183], v[126:129]
	v_mfma_f32_16x16x32_bf16 v[122:125], v[156:159], v[180:183], v[122:125]
	v_mfma_f32_16x16x32_bf16 v[110:113], v[134:137], v[188:191], v[110:113]
	v_mfma_f32_16x16x32_bf16 v[106:109], v[156:159], v[188:191], v[106:109]
	v_mfma_f32_16x16x32_bf16 v[94:97], v[134:137], v[196:199], v[94:97]
	v_mfma_f32_16x16x32_bf16 v[90:93], v[156:159], v[196:199], v[90:93]
	v_mfma_f32_16x16x32_bf16 v[78:81], v[134:137], v[226:229], v[78:81]
	v_mfma_f32_16x16x32_bf16 v[74:77], v[156:159], v[226:229], v[74:77]
	s_setprio 0
	s_setprio 1
	v_mfma_f32_16x16x32_bf16 v[118:121], v[160:163], v[176:179], v[118:121]
	v_mfma_f32_16x16x32_bf16 v[114:117], v[168:171], v[176:179], v[114:117]
	v_mfma_f32_16x16x32_bf16 v[102:105], v[160:163], v[184:187], v[102:105]
	v_mfma_f32_16x16x32_bf16 v[98:101], v[168:171], v[184:187], v[98:101]
	v_mfma_f32_16x16x32_bf16 v[86:89], v[160:163], v[192:195], v[86:89]
	v_mfma_f32_16x16x32_bf16 v[82:85], v[168:171], v[192:195], v[82:85]
	v_mfma_f32_16x16x32_bf16 v[70:73], v[160:163], v[200:203], v[70:73]
	v_mfma_f32_16x16x32_bf16 v[66:69], v[168:171], v[200:203], v[66:69]
	v_mfma_f32_16x16x32_bf16 v[118:121], v[164:167], v[180:183], v[118:121]
	v_mfma_f32_16x16x32_bf16 v[114:117], v[172:175], v[180:183], v[114:117]
	v_mfma_f32_16x16x32_bf16 v[102:105], v[164:167], v[188:191], v[102:105]
	v_mfma_f32_16x16x32_bf16 v[98:101], v[172:175], v[188:191], v[98:101]
	v_mfma_f32_16x16x32_bf16 v[86:89], v[164:167], v[196:199], v[86:89]
	v_mfma_f32_16x16x32_bf16 v[82:85], v[172:175], v[196:199], v[82:85]
	v_mfma_f32_16x16x32_bf16 v[70:73], v[164:167], v[226:229], v[70:73]
	v_mfma_f32_16x16x32_bf16 v[66:69], v[172:175], v[226:229], v[66:69]
	s_setprio 0
	s_barrier
	s_add_i32 s10, s33, s29
	s_mov_b32 m0, s10
	s_add_u32 s98, s98, 0x80
	s_addc_u32 s99, s99, 0
	ds_read_b128 v[176:179], v225 offset:49152
	ds_read_b128 v[180:183], v225 offset:50176
	ds_read_b128 v[184:187], v225 offset:51200
	ds_read_b128 v[188:191], v225 offset:52224
	ds_read_b128 v[192:195], v225 offset:53248
	ds_read_b128 v[196:199], v225 offset:54272
	ds_read_b128 v[200:203], v225 offset:55296
	ds_read_b128 v[226:229], v225 offset:56320
	global_load_lds_dwordx4 v0, s[98:99]
	s_add_i32 m0, s10, 0x2000
	s_add_i32 s10, s34, s29
	global_load_lds_dwordx4 v150, s[98:99]
	s_mov_b32 m0, s10
	s_add_u32 s72, s72, 0x80
	s_addc_u32 s73, s73, 0
	global_load_lds_dwordx4 v0, s[72:73]
	s_add_i32 m0, s10, 0x2000
	s_add_u32 s100, s100, 0x80
	s_addc_u32 s101, s101, 0
	global_load_lds_dwordx4 v150, s[72:73]
	s_mov_b32 m0, s96
	s_nop 0
	global_load_lds_dwordx4 v146, s[100:101]
	s_mov_b32 m0, s97
	s_nop 0
	global_load_lds_dwordx4 v148, s[100:101]
	s_waitcnt vmcnt(8)
	s_waitcnt lgkmcnt(0)
	s_barrier
	s_setprio 1
	s_waitcnt lgkmcnt(0)
	v_mfma_f32_16x16x32_bf16 v[62:65], v[130:133], v[176:179], v[62:65]
	v_mfma_f32_16x16x32_bf16 v[58:61], v[138:141], v[176:179], v[58:61]
	v_mfma_f32_16x16x32_bf16 v[46:49], v[130:133], v[184:187], v[46:49]
	v_mfma_f32_16x16x32_bf16 v[42:45], v[138:141], v[184:187], v[42:45]
	v_mfma_f32_16x16x32_bf16 v[30:33], v[130:133], v[192:195], v[30:33]
	v_mfma_f32_16x16x32_bf16 v[26:29], v[138:141], v[192:195], v[26:29]
	v_mfma_f32_16x16x32_bf16 v[14:17], v[130:133], v[200:203], v[14:17]
	v_mfma_f32_16x16x32_bf16 v[10:13], v[138:141], v[200:203], v[10:13]
	v_mfma_f32_16x16x32_bf16 v[62:65], v[134:137], v[180:183], v[62:65]
	v_mfma_f32_16x16x32_bf16 v[58:61], v[156:159], v[180:183], v[58:61]
	v_mfma_f32_16x16x32_bf16 v[46:49], v[134:137], v[188:191], v[46:49]
	v_mfma_f32_16x16x32_bf16 v[42:45], v[156:159], v[188:191], v[42:45]
	v_mfma_f32_16x16x32_bf16 v[30:33], v[134:137], v[196:199], v[30:33]
	v_mfma_f32_16x16x32_bf16 v[26:29], v[156:159], v[196:199], v[26:29]
	v_mfma_f32_16x16x32_bf16 v[14:17], v[134:137], v[226:229], v[14:17]
	v_mfma_f32_16x16x32_bf16 v[10:13], v[156:159], v[226:229], v[10:13]
	s_setprio 0
	s_setprio 1
	v_mfma_f32_16x16x32_bf16 v[54:57], v[160:163], v[176:179], v[54:57]
	v_mfma_f32_16x16x32_bf16 v[50:53], v[168:171], v[176:179], v[50:53]
	v_mfma_f32_16x16x32_bf16 v[38:41], v[160:163], v[184:187], v[38:41]
	v_mfma_f32_16x16x32_bf16 v[34:37], v[168:171], v[184:187], v[34:37]
	v_mfma_f32_16x16x32_bf16 v[22:25], v[160:163], v[192:195], v[22:25]
	v_mfma_f32_16x16x32_bf16 v[18:21], v[168:171], v[192:195], v[18:21]
	v_mfma_f32_16x16x32_bf16 v[6:9], v[160:163], v[200:203], v[6:9]
	v_mfma_f32_16x16x32_bf16 v[2:5], v[168:171], v[200:203], v[2:5]
	v_mfma_f32_16x16x32_bf16 v[54:57], v[164:167], v[180:183], v[54:57]
	v_mfma_f32_16x16x32_bf16 v[50:53], v[172:175], v[180:183], v[50:53]
	v_mfma_f32_16x16x32_bf16 v[38:41], v[164:167], v[188:191], v[38:41]
	v_mfma_f32_16x16x32_bf16 v[34:37], v[172:175], v[188:191], v[34:37]
	v_mfma_f32_16x16x32_bf16 v[22:25], v[164:167], v[196:199], v[22:25]
	v_mfma_f32_16x16x32_bf16 v[18:21], v[172:175], v[196:199], v[18:21]
	v_mfma_f32_16x16x32_bf16 v[6:9], v[164:167], v[226:229], v[6:9]
	v_mfma_f32_16x16x32_bf16 v[2:5], v[172:175], v[226:229], v[2:5]
	s_setprio 0
	s_barrier
	s_add_u32 s57, s57, 0x100
	s_addc_u32 vcc_lo, vcc_lo, 0
	s_add_u32 s38, s38, 0x100
	s_addc_u32 s39, s39, 0
	s_cmp_ge_u32 s52, s22
	s_mov_b32 s10, s52
	s_cbranch_scc0 .LBB0_692

	.amdhsa_kernel _Z8mega_fwd6Params
		.amdhsa_group_segment_fixed_size 0
		.amdhsa_private_segment_fixed_size 0
		.amdhsa_kernarg_size 536
		.amdhsa_user_sgpr_count 2
		.amdhsa_user_sgpr_dispatch_ptr 0
		.amdhsa_user_sgpr_queue_ptr 0
		.amdhsa_user_sgpr_kernarg_segment_ptr 1
		.amdhsa_user_sgpr_dispatch_id 0
		.amdhsa_user_sgpr_kernarg_preload_length 0
		.amdhsa_user_sgpr_kernarg_preload_offset 0
		.amdhsa_user_sgpr_private_segment_size 0
		.amdhsa_uses_dynamic_stack 0
		.amdhsa_enable_private_segment 0
		.amdhsa_system_sgpr_workgroup_id_x 1
		.amdhsa_system_sgpr_workgroup_id_y 0
		.amdhsa_system_sgpr_workgroup_id_z 0
		.amdhsa_system_sgpr_workgroup_info 0
		.amdhsa_system_vgpr_workitem_id 2
		.amdhsa_next_free_vgpr 246
		.amdhsa_next_free_sgpr 102
		.amdhsa_accum_offset 248
		.amdhsa_reserve_vcc 1
		.amdhsa_float_round_mode_32 0
		.amdhsa_float_round_mode_16_64 0
		.amdhsa_float_denorm_mode_32 3
		.amdhsa_float_denorm_mode_16_64 3
		.amdhsa_dx10_clamp 1
		.amdhsa_ieee_mode 1
		.amdhsa_fp16_overflow 0
		.amdhsa_tg_split 0
		.amdhsa_exception_fp_ieee_invalid_op 0
		.amdhsa_exception_fp_denorm_src 0
		.amdhsa_exception_fp_ieee_div_zero 0
		.amdhsa_exception_fp_ieee_overflow 0
		.amdhsa_exception_fp_ieee_underflow 0
		.amdhsa_exception_fp_ieee_inexact 0
		.amdhsa_exception_int_div_zero 0
	.end_amdhsa_kernel

amdhsa.kernels:
  - .agpr_count:     0
    .args:
      - .offset:         0
        .size:           280
        .value_kind:     by_value
      - .offset:         280
        .size:           4
        .value_kind:     hidden_block_count_x
      - .offset:         284
        .size:           4
        .value_kind:     hidden_block_count_y
      - .offset:         288
        .size:           4
        .value_kind:     hidden_block_count_z
      - .offset:         292
        .size:           2
        .value_kind:     hidden_group_size_x
      - .offset:         294
        .size:           2
        .value_kind:     hidden_group_size_y
      - .offset:         296
        .size:           2
        .value_kind:     hidden_group_size_z
      - .offset:         298
        .size:           2
        .value_kind:     hidden_remainder_x
      - .offset:         300
        .size:           2
        .value_kind:     hidden_remainder_y
      - .offset:         302
        .size:           2
        .value_kind:     hidden_remainder_z
      - .offset:         320
        .size:           8
        .value_kind:     hidden_global_offset_x
      - .offset:         328
        .size:           8
        .value_kind:     hidden_global_offset_y
      - .offset:         336
        .size:           8
        .value_kind:     hidden_global_offset_z
      - .offset:         344
        .size:           2
        .value_kind:     hidden_grid_dims
      - .offset:         368
        .size:           8
        .value_kind:     hidden_multigrid_sync_arg
      - .offset:         400
        .size:           4
        .value_kind:     hidden_dynamic_lds_size
    .group_segment_fixed_size: 0
    .kernarg_segment_align: 8
    .kernarg_segment_size: 536
    .language:       OpenCL C
    .language_version:
      - 2
      - 0
    .max_flat_workgroup_size: 512
    .name:           _Z8mega_fwd6Params
    .private_segment_fixed_size: 0
    .sgpr_count:     108
    .sgpr_spill_count: 116
    .symbol:         _Z8mega_fwd6Params.kd
    .uniform_work_group_size: 1
    .uses_dynamic_stack: false
    .vgpr_count:     246
    .vgpr_spill_count: 0
    .wavefront_size: 64
